# grid barrier between the two RG-LRU sweeps replaced by a pairwise flag hand-off (XC stored/read with sc1)
# speedup vs baseline: 1.0023x; 1.0023x over previous
.LBB0_365:
	v_cndmask_b32_e64 v24, v21, v9, s[2:3]
	v_cndmask_b32_e64 v21, v9, v21, s[2:3]
	v_cndmask_b32_e64 v9, v20, v8, s[2:3]
	v_cndmask_b32_e64 v8, v8, v20, s[2:3]
	v_cndmask_b32_e64 v20, v19, v12, s[2:3]
	v_cndmask_b32_e64 v19, v12, v19, s[2:3]
	v_cndmask_b32_e64 v12, v18, v10, s[2:3]
	v_cndmask_b32_e64 v10, v10, v18, s[2:3]
	v_cndmask_b32_e64 v18, v17, v14, s[2:3]
	v_cndmask_b32_e64 v17, v14, v17, s[2:3]
	v_cndmask_b32_e64 v14, v15, v13, s[2:3]
	v_cndmask_b32_e64 v13, v13, v15, s[2:3]
	s_waitcnt lgkmcnt(0)
	v_fmac_f32_e32 v13, v17, v11
	v_fmac_f32_e32 v14, v18, v13
	v_fmac_f32_e32 v10, v19, v14
	v_fmac_f32_e32 v12, v20, v10
	v_fmac_f32_e32 v8, v21, v12
	v_cndmask_b32_e64 v23, v1, v6, s[2:3]
	v_cndmask_b32_e64 v22, v0, v7, s[2:3]
	v_fmac_f32_e32 v9, v24, v8
	v_fmac_f32_e32 v22, v23, v9
	s_and_saveexec_b64 s[0:1], s[52:53]
	s_cbranch_execz .LBB0_368
	s_add_i32 s5, s25, 64
	v_cndmask_b32_e64 v1, v6, v1, s[2:3]
	v_cndmask_b32_e64 v0, v7, v0, s[2:3]
	s_and_b32 s5, s5, 64
	v_fmac_f32_e32 v0, v1, v22
	v_lshl_add_u32 v1, s5, 2, v141
	s_andn2_b64 vcc, exec, s[94:95]
	ds_write_b32 v1, v0
	s_cbranch_vccnz .LBB0_368
	global_store_dword v[108:109], v0, off sc1

.LBB0_498:
	s_cmp_lg_u32 s98, 0
	s_cbranch_scc1 .Lwq_ret
	s_waitcnt vmcnt(0)
	s_barrier
	s_and_saveexec_b64 s[0:1], s[56:57]
	v_readlane_b32 s30, v254, 5
	v_readlane_b32 s31, v254, 6
	s_cbranch_execz .LBB0_550
	v_readlane_b32 s2, v254, 4
	s_lshl_b32 s3, s2, 2
	s_xor_b32 s4, s2, 8
	s_lshl_b32 s4, s4, 2
	v_mov_b32_e32 v0, s3
	v_add_u32_e32 v0, 0x8000, v0
	v_mov_b32_e32 v1, 1
	v_mov_b32_e32 v3, s4
	v_add_u32_e32 v3, 0x8000, v3
	s_waitcnt vmcnt(0) lgkmcnt(0)
	global_atomic_add v0, v1, s[78:79]
.Lmb_poll:
	global_load_dword v2, v3, s[78:79] sc1
	s_waitcnt vmcnt(0)
	v_cmp_eq_u32_e32 vcc, 0, v2
	s_cbranch_vccz .Lmb_go
	s_sleep 1
	s_branch .Lmb_poll
.Lmb_go:
.LBB0_550:
	s_or_b64 exec, exec, s[0:1]
	v_readlane_b32 s0, v254, 9
	v_readlane_b32 s1, v254, 10
	s_andn2_b64 vcc, exec, s[0:1]
	v_readfirstlane_b32 s8, v195
	s_waitcnt lgkmcnt(0)
	s_barrier
	s_cbranch_vccnz .LBB0_602
	s_lshl_b32 s0, s8, 3
	s_andn2_b32 s0, s0, 31
	v_mov_b32_e32 v32, 0
	v_or_b32_e32 v102, s0, v196
	s_movk_i32 s0, 0x140
	v_lshlrev_b32_e32 v0, 2, v193
	v_mov_b32_e32 v1, v32
	v_lshlrev_b32_e32 v103, 4, v193
	v_cmp_gt_u32_e64 s[2:3], s0, v193
	v_lshl_add_u64 v[2:3], s[78:79], 0, v[0:1]
	s_mov_b64 s[0:1], 0x6c00000
	v_and_b32_e32 v104, 48, v103
	s_add_i32 s6, 0, 0x15800
	v_lshl_add_u64 v[76:77], v[2:3], 0, s[0:1]
	s_add_i32 s0, 0, 0x15d00
	s_and_b32 s9, s8, 3
	v_add_u32_e32 v105, s6, v0
	v_add_u32_e32 v106, s0, v0
	v_lshlrev_b32_e32 v0, 2, v104
	v_lshlrev_b32_e32 v4, 2, v102
	s_add_i32 s1, 0, 0x15c00
	v_add_u32_e32 v109, s6, v0
	v_lshlrev_b32_e32 v2, 7, v194
	s_add_i32 s11, 0, 0x10800
	v_lshlrev_b32_e32 v3, 1, v104
	s_lshl_b32 s6, s9, 5
	v_add_u32_e32 v112, s0, v4
	s_lshl_b32 s0, s9, 6
	s_add_i32 s24, 0, 0x15000
	s_add_i32 s25, 0, 0x14800
	v_add_u32_e32 v108, s1, v0
	s_movk_i32 s1, 0x110
	v_add_u32_e32 v0, 0, v0
	v_add3_u32 v111, s11, v2, v3
	v_or_b32_e32 v2, s6, v196
	v_lshrrev_b32_e32 v5, 3, v193
	s_cmp_eq_u32 s9, 3
	v_mad_u32_u24 v110, v194, s1, v0
	v_mad_u32_u24 v2, v2, s1, 0
	v_and_or_b32 v113, v5, 4, s6
	v_cmp_gt_u32_e64 s[6:7], 32, v192
	v_add_lshl_u32 v6, v102, s0, 2
	s_cselect_b64 s[0:1], -1, 0
	s_cmp_lg_u32 s9, 3
	s_cselect_b64 s[12:13], -1, 0
	s_and_b64 s[14:15], s[6:7], s[0:1]
	s_cmp_eq_u32 s9, 0
	s_movk_i32 s10, 0x100
	s_cselect_b64 s[16:17], -1, 0
	s_cmp_lg_u32 s9, 0
	v_add_u32_e32 v7, 0x100, v4
	v_add_u32_e32 v5, 0, v4
	s_cselect_b64 s[18:19], -1, 0
	s_lshl_b32 s8, s8, 10
	v_add_u32_e32 v117, s25, v4
	v_add_u32_e32 v118, s24, v4
	v_add_u32_e32 v119, s25, v7
	v_add_u32_e32 v120, s24, v7
	v_add_u32_e32 v7, 0x200, v4
	v_add_u32_e32 v4, 0x300, v4
	v_cmp_gt_u32_e32 vcc, s10, v193
	s_and_b64 s[34:35], s[6:7], s[16:17]
	s_and_b32 s8, s8, 0xfffff000
	v_add_u32_e32 v139, s25, v4
	v_add_u32_e32 v140, s24, v4
	v_cndmask_b32_e32 v4, 0, v206, vcc
	s_cmp_gt_u32 s9, 1
	v_add_u32_e32 v121, s25, v7
	v_add_u32_e32 v122, s24, v7
	v_or_b32_e32 v141, v4, v192
	v_mov_b32_e32 v4, s23
	v_mov_b32_e32 v7, s21
	s_cselect_b64 s[36:37], -1, 0
	s_cmp_lt_u32 s9, 2
	v_cndmask_b32_e32 v79, v4, v7, vcc
	v_mov_b32_e32 v4, s22
	v_mov_b32_e32 v7, s20
	v_mul_u32_u24_e32 v1, 0x110, v194
	v_and_b32_e32 v3, 32, v193
	v_add_u32_e32 v114, s24, v6
	v_add_u32_e32 v115, s25, v6
	v_mul_u32_u24_e32 v6, 0x110, v113
	v_lshlrev_b32_e32 v123, 7, v113
	s_cselect_b64 s[42:43], -1, 0
	v_cndmask_b32_e32 v78, v4, v7, vcc
	v_add_u32_e32 v4, 0, v103
	s_add_u32 s20, s78, 0x180000
	v_readlane_b32 s64, v254, 4
	v_cmp_gt_u32_e64 s[4:5], 64, v193
	v_add_u32_e32 v107, 0x780, v194
	v_lshl_add_u32 v116, v102, 1, s11
	v_or_b32_e32 v124, 0x80, v123
	v_or_b32_e32 v125, 0x100, v123
	v_or_b32_e32 v126, 0x180, v123
	v_or_b32_e32 v127, 0x400, v123
	v_or_b32_e32 v128, 0x480, v123
	v_or_b32_e32 v129, 0x500, v123
	v_or_b32_e32 v130, 0x580, v123
	v_or_b32_e32 v131, 0x800, v123
	v_or_b32_e32 v132, 0x880, v123
	v_or_b32_e32 v133, 0x900, v123
	v_or_b32_e32 v134, 0x980, v123
	v_or_b32_e32 v135, 0xc00, v123
	v_or_b32_e32 v136, 0xc80, v123
	v_or_b32_e32 v137, 0xd00, v123
	v_or_b32_e32 v138, 0xd80, v123
	v_add_u32_e32 v142, 0x8800, v4
	v_add_u32_e32 v143, 0xfffffe00, v193
	s_addc_u32 s21, s79, 0
	s_mov_b64 s[22:23], 0x2000
	s_mov_b32 s24, 0x41700000
	s_mov_b32 s25, 0x3f2aaaab
	v_mov_b32_e32 v144, 0x3ecc95a3
	s_mov_b32 s30, 0x3f317218
	s_mov_b32 s31, 0x7f800000
	s_mov_b32 s33, 0x33800000
	s_movk_i32 s54, 0xe00
	s_mov_b32 s55, 0x3e800000
	s_movk_i32 s58, 0x1000
	v_add_u32_e32 v145, v2, v3
	v_add_u32_e32 v146, s8, v197
	v_mov_b32_e32 v147, 0x3d2aaaab
	s_mov_b32 s59, 0xbe800000
	v_add_u32_e32 v148, v0, v1
	s_mov_b64 s[46:47], 0x1e400400
	s_mov_b32 s62, 0x1e400000
	v_mov_b32_e32 v80, 0x3f317218
	v_mov_b32_e32 v149, 0x7f800000
	v_mov_b32_e32 v150, 0x7fc00000
	v_mov_b32_e32 v151, 0xff800000
	v_mov_b32_e32 v152, 0xe00
	v_add_u32_e32 v153, v5, v6
	s_mov_b32 s63, s64
	s_branch .LBB0_553

.LBB0_553:
	s_and_b32 s48, s64, 7
	s_lshl_b32 s11, s48, 6
	s_barrier
	s_and_saveexec_b64 s[8:9], s[2:3]
	v_or_b32_e32 v0, s11, v141
	v_lshlrev_b32_e32 v0, 2, v0
	v_mov_b32_e32 v1, v32
	v_lshl_add_u64 v[0:1], v[78:79], 0, v[0:1]
	global_load_dword v244, v[0:1], off
	s_or_b64 exec, exec, s[8:9]
	s_lshr_b32 s10, s64, 3
	s_bitcmp1_b32 s64, 3
	s_cselect_b64 s[8:9], -1, 0
	s_xor_b64 s[8:9], s[8:9], -1
	v_cndmask_b32_e64 v0, 0, 1, s[8:9]
	s_and_b32 s8, s63, 7
	v_lshl_or_b32 v0, v0, 17, v103
	v_lshl_or_b32 v0, s8, 14, v0
	v_mov_b32_e32 v1, v32
	v_lshl_add_u64 v[0:1], s[20:21], 0, v[0:1]
	global_load_dwordx4 v[236:239], v[0:1], off
	v_lshl_add_u64 v[0:1], v[0:1], 0, s[22:23]
	global_load_dwordx4 v[240:243], v[0:1], off
	s_and_b32 s10, s10, 1
	s_xor_b32 s49, s10, 1
	s_and_saveexec_b64 s[8:9], s[4:5]
	s_lshl_b32 s48, s48, 1
	s_and_b32 s50, s64, -16
	s_or_b32 s48, s48, s50
	s_or_b32 s50, s48, s49
	s_ashr_i32 s51, s50, 31
	s_lshl_b64 s[50:51], s[50:51], 8
	v_lshl_add_u64 v[0:1], v[76:77], 0, s[50:51]
	global_load_dword v245, v[0:1], off sc1
	s_or_b64 exec, exec, s[8:9]
	v_add_u32_e32 v0, s11, v102
	v_lshl_add_u32 v2, s49, 9, v0
	v_ashrrev_i32_e32 v3, 31, v2
	v_lshlrev_b64 v[2:3], 2, v[2:3]
	v_lshl_add_u64 v[4:5], s[40:41], 0, v[2:3]
	global_load_dword v6, v[4:5], off
	v_lshl_add_u64 v[4:5], s[26:27], 0, v[2:3]
	v_lshl_add_u64 v[2:3], s[38:39], 0, v[2:3]
	global_load_dword v1, v[4:5], off
	global_load_dword v2, v[2:3], off
	s_waitcnt vmcnt(0)
	s_and_saveexec_b64 s[8:9], s[2:3]
	ds_write_b32 v105, v244
	s_or_b64 exec, exec, s[8:9]
	ds_write_b128 v142, v[236:239]
	ds_write_b128 v142, v[240:243] offset:8192
	s_and_saveexec_b64 s[8:9], s[4:5]
	ds_write_b32 v106, v245
	s_or_b64 exec, exec, s[8:9]
	v_cmp_nlt_f32_e32 vcc, s24, v6
	v_mul_f32_e32 v3, 0xbfb8aa3b, v6
	v_exp_f32_e32 v3, v3
	s_and_saveexec_b64 s[8:9], vcc
	s_cbranch_execz .LBB0_561
	v_add_f32_e32 v6, 1.0, v3
	v_add_f32_e32 v4, -1.0, v6
	v_sub_f32_e32 v5, v4, v6
	v_add_f32_e32 v5, 1.0, v5
	v_sub_f32_e32 v4, v3, v4
	v_add_f32_e32 v7, v4, v5
	v_frexp_mant_f32_e32 v8, v6
	v_cvt_f64_f32_e32 v[4:5], v6
	v_frexp_exp_i32_f64_e32 v4, v[4:5]
	v_cmp_gt_f32_e32 vcc, s25, v8
	s_nop 1
	v_subbrev_co_u32_e32 v12, vcc, 0, v4, vcc
	v_sub_u32_e32 v4, 0, v12
	v_ldexp_f32 v5, v6, v4
	v_add_f32_e32 v6, -1.0, v5
	v_add_f32_e32 v8, 1.0, v5
	v_ldexp_f32 v4, v7, v4
	v_add_f32_e32 v7, 1.0, v6
	v_add_f32_e32 v9, -1.0, v8
	v_sub_f32_e32 v7, v5, v7
	v_sub_f32_e32 v5, v5, v9
	v_add_f32_e32 v7, v4, v7
	v_add_f32_e32 v4, v4, v5
	v_add_f32_e32 v13, v8, v4
	v_rcp_f32_e32 v15, v13
	v_sub_f32_e32 v5, v13, v8
	v_sub_f32_e32 v14, v4, v5
	v_add_f32_e32 v5, v6, v7
	v_mul_f32_e32 v17, v5, v15
	v_sub_f32_e32 v4, v5, v6
	v_mul_f32_e32 v6, v13, v17
	v_fma_f32 v8, v17, v13, -v6
	v_fmac_f32_e32 v8, v17, v14
	v_sub_f32_e32 v16, v7, v4
	v_add_f32_e32 v4, v6, v8
	v_sub_f32_e32 v7, v5, v4
	v_pk_add_f32 v[10:11], v[4:5], v[6:7] neg_lo:[0,1] neg_hi:[0,1]
	v_mov_b32_e32 v9, v4
	v_pk_add_f32 v[4:5], v[10:11], v[8:9] neg_lo:[0,1] neg_hi:[0,1]
	v_cmp_neq_f32_e32 vcc, s31, v3
	v_add_f32_e32 v5, v16, v5
	v_add_f32_e32 v4, v4, v5
	v_add_f32_e32 v5, v7, v4
	v_mul_f32_e32 v16, v15, v5
	v_mul_f32_e32 v6, v13, v16
	v_fma_f32 v8, v16, v13, -v6
	v_fmac_f32_e32 v8, v16, v14
	v_sub_f32_e32 v7, v7, v5
	v_add_f32_e32 v13, v4, v7
	v_add_f32_e32 v4, v6, v8
	v_sub_f32_e32 v7, v5, v4
	v_pk_add_f32 v[10:11], v[4:5], v[6:7] neg_lo:[0,1] neg_hi:[0,1]
	v_mov_b32_e32 v9, v4
	v_pk_add_f32 v[4:5], v[10:11], v[8:9] neg_lo:[0,1] neg_hi:[0,1]
	s_nop 0
	v_add_f32_e32 v5, v13, v5
	v_add_f32_e32 v4, v4, v5
	v_add_f32_e32 v5, v17, v16
	v_add_f32_e32 v4, v7, v4
	v_sub_f32_e32 v6, v5, v17
	v_mul_f32_e32 v4, v15, v4
	v_sub_f32_e32 v6, v16, v6
	v_add_f32_e32 v6, v6, v4
	v_add_f32_e32 v8, v5, v6
	v_mul_f32_e32 v9, v8, v8
	v_fmamk_f32 v4, v9, 0x3e9b6dac, v144
	v_fmaak_f32 v81, v9, v4, 0x3f2aaada
	v_cvt_f32_i32_e32 v4, v12
	v_sub_f32_e32 v5, v8, v5
	v_sub_f32_e32 v5, v6, v5
	v_ldexp_f32 v10, v5, 1
	v_mul_f32_e32 v5, v8, v9
	v_ldexp_f32 v7, v8, 1
	v_pk_mul_f32 v[8:9], v[4:5], v[80:81]
	s_nop 0
	v_fma_f32 v6, v4, s30, -v8
	v_fmac_f32_e32 v6, 0xb102e308, v4
	v_pk_add_f32 v[4:5], v[8:9], v[6:7]
	s_nop 0
	v_sub_f32_e32 v7, v5, v7
	v_sub_f32_e32 v7, v9, v7
	v_add_f32_e32 v11, v10, v7
	v_mov_b32_e32 v10, v8
	v_pk_add_f32 v[8:9], v[4:5], v[8:9] neg_lo:[0,1] neg_hi:[0,1]
	v_pk_add_f32 v[12:13], v[4:5], v[10:11]
	v_mov_b32_e32 v7, v4
	v_mov_b32_e32 v9, v13
	v_pk_add_f32 v[14:15], v[6:7], v[8:9] neg_lo:[0,1] neg_hi:[0,1]
	v_pk_add_f32 v[6:7], v[6:7], v[8:9]
	v_mov_b32_e32 v10, v11
	v_pk_add_f32 v[8:9], v[6:7], v[4:5] op_sel:[1,0] op_sel_hi:[0,1] neg_lo:[0,1] neg_hi:[0,1]
	v_pk_add_f32 v[16:17], v[12:13], v[8:9] op_sel_hi:[1,0] neg_lo:[0,1] neg_hi:[0,1]
	v_mov_b32_e32 v12, v13
	v_mov_b32_e32 v13, v7
	v_pk_mov_b32 v[8:9], v[4:5], v[8:9] op_sel:[1,0]
	v_mov_b32_e32 v11, v4
	v_pk_add_f32 v[8:9], v[12:13], v[8:9] neg_lo:[0,1] neg_hi:[0,1]
	v_mov_b32_e32 v16, v14
	v_pk_add_f32 v[4:5], v[10:11], v[8:9] neg_lo:[0,1] neg_hi:[0,1]
	v_mov_b32_e32 v15, v7
	v_pk_add_f32 v[8:9], v[16:17], v[4:5]
	s_nop 0
	v_pk_add_f32 v[10:11], v[8:9], v[8:9] op_sel:[0,1] op_sel_hi:[1,0]
	s_nop 0
	v_pk_add_f32 v[6:7], v[6:7], v[10:11] op_sel:[1,0] op_sel_hi:[0,1]
	v_mov_b32_e32 v9, v6
	v_pk_add_f32 v[12:13], v[8:9], v[14:15] neg_lo:[0,1] neg_hi:[0,1]
	v_mov_b32_e32 v5, v10
	v_sub_f32_e32 v7, v8, v12
	v_pk_add_f32 v[4:5], v[4:5], v[12:13] neg_lo:[0,1] neg_hi:[0,1]
	v_sub_f32_e32 v7, v14, v7
	v_add_f32_e32 v4, v4, v7
	v_add_f32_e32 v4, v4, v5
	v_add_f32_e32 v4, v6, v4
	v_cndmask_b32_e32 v4, v149, v4, vcc
	v_cmp_ngt_f32_e32 vcc, -1.0, v3
	s_nop 1
	v_cndmask_b32_e32 v4, v150, v4, vcc
	v_cmp_neq_f32_e32 vcc, -1.0, v3
	s_nop 1
	v_cndmask_b32_e32 v4, v151, v4, vcc
	v_cmp_lt_f32_e64 vcc, |v3|, s33
	s_nop 1
	v_cndmask_b32_e32 v3, v4, v3, vcc
